# layer-boundary barrier: leader's L1 invalidate issued right after its L2 write-back, before it waits for the other XCD leaders
# baseline (speedup 1.0000x reference)
.LBB0_1066:
	s_andn2_saveexec_b64 s[2:3], s[2:3]
	s_cbranch_execz .LBB0_1086
	s_mov_b64 s[2:3], exec
	buffer_wbl2 sc1
	s_waitcnt lgkmcnt(0)
	s_waitcnt vmcnt(0)
	buffer_inv sc1
	v_mbcnt_lo_u32_b32 v1, s2, 0
	v_mbcnt_hi_u32_b32 v1, s3, v1
	v_cmp_eq_u32_e32 vcc, 0, v1
	s_and_saveexec_b64 s[8:9], vcc
	s_cbranch_execz .LBB0_1069
	s_bcnt1_i32_b64 s2, s[2:3]
	v_mov_b32_e32 v2, s2
	v_readlane_b32 s2, v252, 56
	v_readlane_b32 s3, v252, 57
	s_nop 4
	global_atomic_add v2, v193, v2, s[2:3] sc0
